# attention main loop: the two self-max canonicalisations on the serial row-max chain before the rescale branch dropped
# baseline (speedup 1.0000x reference)
.LBB0_1316:
	v_add_u32_e32 v0, s16, v240
	ds_read_b64_tr_b16 v[192:193], v0 offset:24576
	ds_read_b64_tr_b16 v[194:195], v0 offset:25088
	v_add_f32_e32 v2, v80, v81
	v_add_f32_e32 v2, v82, v2
	v_add_f32_e32 v2, v83, v2
	v_add_f32_e32 v2, v84, v2
	v_add_f32_e32 v2, v85, v2
	v_cvt_pk_bf16_f32 v156, v80, v81
	v_cvt_pk_bf16_f32 v157, v82, v83
	s_waitcnt lgkmcnt(9)
	v_mfma_f32_32x32x16_bf16 v[96:111], v[188:191], v[140:143], v[48:63]
	ds_read_b64_tr_b16 v[188:189], v0 offset:28672
	ds_read_b64_tr_b16 v[190:191], v0 offset:29184
	v_add_f32_e32 v2, v86, v2
	v_add_f32_e32 v2, v87, v2
	v_add_f32_e32 v2, v88, v2
	v_add_f32_e32 v2, v89, v2
	v_cvt_pk_bf16_f32 v158, v84, v85
	v_cvt_pk_bf16_f32 v159, v86, v87
	s_waitcnt lgkmcnt(10)
	v_mfma_f32_32x32x16_bf16 v[112:127], v[184:187], v[140:143], v[48:63]
	ds_read_b64_tr_b16 v[10:11], v0 offset:25600
	ds_read_b64_tr_b16 v[12:13], v0 offset:26112
	v_add_f32_e32 v2, v90, v2
	v_add_f32_e32 v2, v91, v2
	v_add_f32_e32 v2, v92, v2
	v_add_f32_e32 v2, v93, v2
	v_cvt_pk_bf16_f32 v152, v88, v89
	v_cvt_pk_bf16_f32 v153, v90, v91
	s_waitcnt lgkmcnt(11)
	v_mfma_f32_32x32x16_bf16 v[96:111], v[180:183], v[136:139], v[96:111]
	ds_read_b64_tr_b16 v[180:181], v0 offset:29696
	ds_read_b64_tr_b16 v[182:183], v0 offset:30208
	v_add_f32_e32 v2, v94, v2
	v_add_f32_e32 v2, v95, v2
	v_add_f32_e32 v2, v64, v2
	v_add_f32_e32 v2, v65, v2
	v_cvt_pk_bf16_f32 v154, v92, v93
	v_cvt_pk_bf16_f32 v155, v94, v95
	s_waitcnt lgkmcnt(12)
	v_mfma_f32_32x32x16_bf16 v[112:127], v[176:179], v[136:139], v[112:127]
	ds_read_b64_tr_b16 v[176:177], v0 offset:26624
	ds_read_b64_tr_b16 v[178:179], v0 offset:27136
	v_add_f32_e32 v2, v66, v2
	v_add_f32_e32 v2, v67, v2
	v_add_f32_e32 v2, v68, v2
	v_add_f32_e32 v6, v69, v2
	v_cvt_pk_bf16_f32 v148, v64, v65
	v_cvt_pk_bf16_f32 v149, v66, v67
	ds_read_b128 v[64:67], v200
	s_waitcnt lgkmcnt(13)
	v_mfma_f32_32x32x16_bf16 v[96:111], v[172:175], v[132:135], v[96:111]
	ds_read_b64_tr_b16 v[2:3], v0 offset:30720
	ds_read_b64_tr_b16 v[4:5], v0 offset:31232
	v_add_f32_e32 v6, v70, v6
	v_add_f32_e32 v6, v71, v6
	v_add_f32_e32 v6, v72, v6
	v_add_f32_e32 v14, v73, v6
	v_cvt_pk_bf16_f32 v150, v68, v69
	v_cvt_pk_bf16_f32 v151, v70, v71
	ds_read_b128 v[68:71], v200 offset:32
	s_waitcnt lgkmcnt(14)
	v_mfma_f32_32x32x16_bf16 v[112:127], v[168:171], v[132:135], v[112:127]
	ds_read_b64_tr_b16 v[6:7], v0 offset:27648
	ds_read_b64_tr_b16 v[8:9], v0 offset:28160
	v_add_f32_e32 v14, v74, v14
	v_add_f32_e32 v14, v75, v14
	v_add_f32_e32 v14, v76, v14
	v_add_f32_e32 v14, v77, v14
	v_cvt_pk_bf16_f32 v144, v72, v73
	v_cvt_pk_bf16_f32 v145, v74, v75
	ds_read_b128 v[72:75], v200 offset:128
	s_waitcnt lgkmcnt(14)
	v_mfma_f32_32x32x16_bf16 v[96:111], v[164:167], v[128:131], v[96:111]
	ds_read_b64_tr_b16 v[164:165], v0 offset:31744
	ds_read_b64_tr_b16 v[166:167], v0 offset:32256
	v_add_f32_e32 v0, v78, v14
	v_add_f32_e32 v0, v79, v0
	v_add_f32_e32 v0, 0, v0
	v_cvt_pk_bf16_f32 v146, v76, v77
	v_cvt_pk_bf16_f32 v147, v78, v79
	v_mfma_f32_32x32x16_bf16 v[112:127], v[160:163], v[128:131], v[112:127]
	s_add_i32 s16, s46, -2
	s_lshr_b32 s16, s16, 2
	s_and_b32 s22, s47, 0x18000
	s_mul_i32 s100, s16, 0x180000
	s_lshl_b32 s26, s22, 1
	s_add_u32 s100, s100, s26
	s_add_u32 s100, s100, s98
	s_addc_u32 s101, s99, 0
	s_add_i32 s16, s50, s74
	s_mov_b32 s17, m0
	s_mov_b32 m0, s16
	s_nop 0
	global_load_lds_dwordx4 v236, s[100:101]
	s_mov_b32 m0, s17
	s_add_i32 s16, s46, -4
	s_add_i32 s17, s47, 0xffff0000
	s_lshr_b32 s16, s16, 2
	s_and_b32 s22, s17, 0x18000
	s_mul_i32 s100, s16, 0x180000
	s_lshl_b32 s26, s22, 1
	s_add_u32 s100, s100, s26
	s_add_u32 s100, s100, s98
	s_addc_u32 s101, s99, 0
	s_add_i32 s16, s25, s75
	s_mov_b32 s17, m0
	s_mov_b32 m0, s16
	s_nop 0
	global_load_lds_dwordx4 v237, s[100:101]
	s_mov_b32 m0, s17
	v_add_f32_e32 v0, v241, v0
	s_waitcnt lgkmcnt(2)
	v_add_f32_e32 v82, v98, v66
	v_add_f32_e32 v83, v99, v67
	s_waitcnt lgkmcnt(1)
	v_add_f32_e32 v84, v100, v68
	v_add_f32_e32 v85, v101, v69
	s_waitcnt lgkmcnt(0)
	v_add_f32_e32 v14, v112, v72
	v_add_f32_e32 v15, v113, v73
	v_add_f32_e32 v66, v114, v74
	v_add_f32_e32 v67, v115, v75
	ds_read_b128 v[72:75], v200 offset:160
	v_add_f32_e32 v86, v102, v70
	v_add_f32_e32 v87, v103, v71
	v_add_f32_e32 v64, v96, v64
	v_add_f32_e32 v65, v97, v65
	v_max3_f32 v81, v82, v83, v15
	v_max_f32_e32 v80, v64, v65
	s_waitcnt lgkmcnt(0)
	v_add_f32_e32 v68, v116, v72
	v_add_f32_e32 v69, v117, v73
	v_add_f32_e32 v70, v118, v74
	v_add_f32_e32 v71, v119, v75
	ds_read_b128 v[72:75], v200 offset:64
	ds_read_b128 v[76:79], v200 offset:192
	v_max3_f32 v80, v80, v14, v66
	v_max3_f32 v80, v80, v67, v84
	v_max3_f32 v81, v81, v86, v87
	s_waitcnt lgkmcnt(1)
	v_add_f32_e32 v88, v104, v72
	v_add_f32_e32 v89, v105, v73
	s_waitcnt lgkmcnt(0)
	v_add_f32_e32 v72, v120, v76
	v_add_f32_e32 v73, v121, v77
	v_add_f32_e32 v90, v106, v74
	v_add_f32_e32 v91, v107, v75
	v_add_f32_e32 v74, v122, v78
	v_add_f32_e32 v75, v123, v79
	ds_read_b128 v[76:79], v200 offset:96
	ds_read_b128 v[94:97], v200 offset:224
	v_max3_f32 v80, v80, v85, v68
	v_max3_f32 v81, v81, v70, v71
	v_max3_f32 v80, v80, v69, v88
	v_max3_f32 v81, v81, v90, v91
	s_waitcnt lgkmcnt(1)
	v_add_f32_e32 v92, v108, v76
	v_add_f32_e32 v93, v109, v77
	s_waitcnt lgkmcnt(0)
	v_add_f32_e32 v76, v124, v94
	v_add_f32_e32 v77, v125, v95
	v_add_f32_e32 v94, v110, v78
	v_add_f32_e32 v95, v111, v79
	v_max3_f32 v80, v80, v89, v72
	v_max3_f32 v81, v81, v74, v75
	v_add_f32_e32 v78, v126, v96
	v_add_f32_e32 v79, v127, v97
	v_max3_f32 v80, v80, v73, v92
	v_max3_f32 v81, v81, v94, v95
	v_max3_f32 v80, v80, v93, v76
	v_max3_f32 v81, v81, v78, v79
	v_max3_f32 v80, v80, v77, v81
	v_mov_b32_e32 v81, v80
	s_nop 1
	v_permlane32_swap_b32_e32 v80, v81
	v_max_f32_e32 v80, v80, v81
	v_cmp_lt_f32_e32 vcc, s36, v80
	s_cmp_lg_u64 vcc, 0
	s_cselect_b64 s[16:17], -1, 0
	s_cbranch_vccnz .LBB0_1324

.LBB0_1319:
	s_add_i32 s16, s25, 0x2000
	s_cmpk_lg_i32 s25, 0x4000
	s_cselect_b32 s78, s16, 0
	v_add_u32_e32 v14, s50, v240
	ds_read_b64_tr_b16 v[168:169], v14 offset:24576
	ds_read_b64_tr_b16 v[170:171], v14 offset:25088
	v_add_f32_e32 v2, v80, v81
	v_add_f32_e32 v2, v82, v2
	v_add_f32_e32 v2, v83, v2
	v_add_f32_e32 v2, v84, v2
	v_add_f32_e32 v2, v85, v2
	v_cvt_pk_bf16_f32 v156, v80, v81
	v_cvt_pk_bf16_f32 v157, v82, v83
	s_waitcnt lgkmcnt(9)
	v_mfma_f32_32x32x16_bf16 v[96:111], v[112:115], v[140:143], v[48:63]
	ds_read_b64_tr_b16 v[164:165], v14 offset:28672
	ds_read_b64_tr_b16 v[166:167], v14 offset:29184
	v_add_f32_e32 v2, v86, v2
	v_add_f32_e32 v2, v87, v2
	v_add_f32_e32 v2, v88, v2
	v_add_f32_e32 v2, v89, v2
	v_cvt_pk_bf16_f32 v158, v84, v85
	v_cvt_pk_bf16_f32 v159, v86, v87
	s_waitcnt lgkmcnt(10)
	v_mfma_f32_32x32x16_bf16 v[112:127], v[160:163], v[140:143], v[48:63]
	ds_read_b64_tr_b16 v[10:11], v14 offset:25600
	ds_read_b64_tr_b16 v[12:13], v14 offset:26112
	v_add_f32_e32 v2, v90, v2
	v_add_f32_e32 v2, v91, v2
	v_add_f32_e32 v2, v92, v2
	v_add_f32_e32 v2, v93, v2
	v_cvt_pk_bf16_f32 v152, v88, v89
	v_cvt_pk_bf16_f32 v153, v90, v91
	s_waitcnt lgkmcnt(11)
	v_mfma_f32_32x32x16_bf16 v[96:111], v[192:195], v[136:139], v[96:111]
	ds_read_b64_tr_b16 v[160:161], v14 offset:29696
	ds_read_b64_tr_b16 v[162:163], v14 offset:30208
	v_add_f32_e32 v2, v94, v2
	v_add_f32_e32 v2, v95, v2
	v_add_f32_e32 v2, v64, v2
	v_add_f32_e32 v2, v65, v2
	v_cvt_pk_bf16_f32 v154, v92, v93
	v_cvt_pk_bf16_f32 v155, v94, v95
	s_waitcnt lgkmcnt(12)
	v_mfma_f32_32x32x16_bf16 v[112:127], v[188:191], v[136:139], v[112:127]
	ds_read_b64_tr_b16 v[196:197], v14 offset:26624
	ds_read_b64_tr_b16 v[198:199], v14 offset:27136
	v_add_f32_e32 v2, v66, v2
	v_add_f32_e32 v2, v67, v2
	v_add_f32_e32 v2, v68, v2
	v_add_f32_e32 v6, v69, v2
	v_cvt_pk_bf16_f32 v148, v64, v65
	v_cvt_pk_bf16_f32 v149, v66, v67
	ds_read_b128 v[64:67], v200 offset:256
	s_waitcnt lgkmcnt(13)
	v_mfma_f32_32x32x16_bf16 v[96:111], v[184:187], v[132:135], v[96:111]
	ds_read_b64_tr_b16 v[2:3], v14 offset:30720
	ds_read_b64_tr_b16 v[4:5], v14 offset:31232
	v_add_f32_e32 v6, v70, v6
	v_add_f32_e32 v6, v71, v6
	v_add_f32_e32 v6, v72, v6
	v_add_f32_e32 v15, v73, v6
	v_cvt_pk_bf16_f32 v150, v68, v69
	v_cvt_pk_bf16_f32 v151, v70, v71
	ds_read_b128 v[68:71], v200 offset:288
	s_waitcnt lgkmcnt(14)
	v_mfma_f32_32x32x16_bf16 v[112:127], v[180:183], v[132:135], v[112:127]
	ds_read_b64_tr_b16 v[6:7], v14 offset:27648
	ds_read_b64_tr_b16 v[8:9], v14 offset:28160
	v_add_f32_e32 v15, v74, v15
	v_add_f32_e32 v15, v75, v15
	v_add_f32_e32 v15, v76, v15
	v_add_f32_e32 v15, v77, v15
	v_cvt_pk_bf16_f32 v144, v72, v73
	v_cvt_pk_bf16_f32 v145, v74, v75
	ds_read_b128 v[72:75], v200 offset:384
	s_waitcnt lgkmcnt(14)
	v_mfma_f32_32x32x16_bf16 v[96:111], v[176:179], v[128:131], v[96:111]
	ds_read_b64_tr_b16 v[192:193], v14 offset:31744
	ds_read_b64_tr_b16 v[194:195], v14 offset:32256
	v_add_f32_e32 v14, v78, v15
	v_add_f32_e32 v14, v79, v14
	v_add_f32_e32 v80, 0, v14
	v_cvt_pk_bf16_f32 v146, v76, v77
	v_cvt_pk_bf16_f32 v147, v78, v79
	v_mfma_f32_32x32x16_bf16 v[112:127], v[172:175], v[128:131], v[112:127]
	s_add_i32 s16, s46, -1
	s_add_i32 s17, s47, 0xfffe8000
	s_lshr_b32 s16, s16, 2
	s_and_b32 s22, s17, 0x18000
	s_mul_i32 s100, s16, 0x180000
	s_lshl_b32 s26, s22, 1
	s_add_u32 s100, s100, s26
	s_add_u32 s100, s100, s98
	s_addc_u32 s101, s99, 0
	s_add_i32 s16, s25, s74
	s_mov_b32 s17, m0
	s_mov_b32 m0, s16
	s_nop 0
	global_load_lds_dwordx4 v236, s[100:101]
	s_mov_b32 m0, s17
	s_add_i32 s50, s46, -3
	s_add_i32 s17, s47, 0xffff8000
	s_lshr_b32 s16, s50, 2
	s_and_b32 s22, s17, 0x18000
	s_mul_i32 s100, s16, 0x180000
	s_lshl_b32 s26, s22, 1
	s_add_u32 s100, s100, s26
	s_add_u32 s100, s100, s98
	s_addc_u32 s101, s99, 0
	s_add_i32 s16, s78, s75
	s_mov_b32 s17, m0
	s_mov_b32 m0, s16
	s_nop 0
	global_load_lds_dwordx4 v237, s[100:101]
	s_mov_b32 m0, s17
	v_add_f32_e32 v241, v0, v80
	s_waitcnt lgkmcnt(2)
	v_add_f32_e32 v82, v98, v66
	v_add_f32_e32 v83, v99, v67
	s_waitcnt lgkmcnt(1)
	v_add_f32_e32 v84, v100, v68
	v_add_f32_e32 v85, v101, v69
	s_waitcnt lgkmcnt(0)
	v_add_f32_e32 v14, v112, v72
	v_add_f32_e32 v15, v113, v73
	v_add_f32_e32 v66, v114, v74
	v_add_f32_e32 v67, v115, v75
	ds_read_b128 v[72:75], v200 offset:416
	v_add_f32_e32 v86, v102, v70
	v_add_f32_e32 v87, v103, v71
	v_add_f32_e32 v64, v96, v64
	v_add_f32_e32 v65, v97, v65
	s_waitcnt lgkmcnt(0)
	v_add_f32_e32 v68, v116, v72
	v_add_f32_e32 v69, v117, v73
	v_add_f32_e32 v70, v118, v74
	v_add_f32_e32 v71, v119, v75
	ds_read_b128 v[72:75], v200 offset:320
	ds_read_b128 v[76:79], v200 offset:448
	v_max_f32_e32 v81, v64, v65
	v_max3_f32 v81, v81, v14, v66
	v_max3_f32 v81, v81, v67, v84
	s_waitcnt lgkmcnt(1)
	v_add_f32_e32 v88, v104, v72
	v_add_f32_e32 v89, v105, v73
	s_waitcnt lgkmcnt(0)
	v_add_f32_e32 v72, v120, v76
	v_add_f32_e32 v73, v121, v77
	v_add_f32_e32 v90, v106, v74
	v_add_f32_e32 v91, v107, v75
	v_add_f32_e32 v74, v122, v78
	v_add_f32_e32 v75, v123, v79
	ds_read_b128 v[76:79], v200 offset:352
	ds_read_b128 v[94:97], v200 offset:480
	v_max3_f32 v81, v81, v85, v68
	v_max3_f32 v81, v81, v69, v88
	v_max3_f32 v81, v81, v89, v72
	s_waitcnt lgkmcnt(1)
	v_add_f32_e32 v92, v108, v76
	v_add_f32_e32 v93, v109, v77
	s_waitcnt lgkmcnt(0)
	v_add_f32_e32 v76, v124, v94
	v_add_f32_e32 v77, v125, v95
	v_add_f32_e32 v94, v110, v78
	v_add_f32_e32 v95, v111, v79
	v_add_f32_e32 v78, v126, v96
	v_add_f32_e32 v79, v127, v97
	v_max3_f32 v96, v82, v83, v15
	v_max3_f32 v96, v96, v86, v87
	v_max3_f32 v96, v96, v70, v71
	v_max3_f32 v96, v96, v90, v91
	v_max3_f32 v96, v96, v74, v75
	v_max3_f32 v81, v81, v73, v92
	v_max3_f32 v96, v96, v94, v95
	v_max3_f32 v81, v81, v93, v76
	v_max3_f32 v96, v96, v78, v79
	v_max3_f32 v0, v81, v77, v96
	v_mov_b32_e32 v80, v0
	s_nop 1
	v_permlane32_swap_b32_e32 v0, v80
	v_max_f32_e32 v0, v0, v80
	v_cmp_lt_f32_e32 vcc, s36, v0
	s_cmp_lg_u64 vcc, 0
	s_cselect_b64 s[16:17], -1, 0
	s_cbranch_vccnz .LBB0_1327
